# attention-queue combine items: all 24 loads of the four token steps issued up front (hipcc had 8 dependent round trips per item)
# baseline (speedup 1.0000x reference)
; __global__ void __launch_bounds__(512, 2) mega(Params p) {
;     ...
;                 QUEUE_BEGIN(512 + 256)
;                     if (item >= 256 && item < 512) {
;                         bf16_t* P = (bf16_t*)(R1 + R_P);
;                         const int qt = 15 - ((item - 256) >> 4), bl = (item >> 3) & 1, h = item & 7;
;                         AttnArgs a; a.Q = P + C_SBQ + h * 64; a.ldq = NINP; a.K = P + C_SBK + h * 64; a.ldk = NINP; a.K2 = nullptr; a.ldk2 = 0;
;                         a.V = P + C_SBV + h * 64; a.ldv = NINP; a.O = (bf16_t*)(R1 + R_OA) + h * 64; a.ldo = 512; a.lse = nullptr; a.ldl = 0;
;                         a.q0 = qt * 256; a.tstride = 1; a.toff = bl * SEQ; a.nk = 0; a.c2 = 0.125f * LOG2E; a.biasg = nullptr;
;                         attn_unit<2>(lds, a);
;                     } else if (item < 256) {
;                         const int qt = 15 - (item >> 4), bl = (item >> 3) & 1, h = item & 7;
;                         bf16_t* kvm = (bf16_t*)(R1 + R_KVM);
;                         AttnArgs a; a.Q = (bf16_t*)(R1 + R_QM) + h * 96; a.ldq = 768; a.K = kvm + h * 128; a.ldk = 1024; a.K2 = (bf16_t*)(R1 + R_P) + C_KR; a.ldk2 = NINP;
;                         a.V = kvm + h * 128 + 64; a.ldv = 1024; a.O = (bf16_t*)(R1 + R_OA) + (size_t)TC * 512 + h * 64; a.ldo = 512; a.lse = nullptr; a.ldl = 0;
;                         a.q0 = qt * 256; a.tstride = 1; a.toff = bl * SEQ; a.nk = 0; a.c2 = 0.10206207261596577f * LOG2E; a.biasg = nullptr;
;                         attn_unit<1>(lds, a);
;                     } else {
;                         const int t0 = (item - 512) * 32;
;                         bf16_t* oc = (bf16_t*)(R1 + R_OA) + (size_t)2 * TC * 512;
;                         const bf16_t* og = (const bf16_t*)(R1 + R_OG);
;                         const float* lse = (const float*)(R1 + R_LSE);
; #pragma unroll
;                         for (int ps = 0; ps < 4; ++ps) {
;                             const int tok = t0 + ps * 8 + (tid >> 6), c8 = (tid & 63) * 8, h = c8 >> 6;
;                             const float l0 = lse[(size_t)tok * 8 + h], l1 = lse[(size_t)(TC + tok) * 8 + h], l2 = lse[(size_t)(2 * TC + tok) * 8 + h];
;                             const float mx = fmaxf(l0, fmaxf(l1, l2));
;                             float w0 = ex2(l0 - mx), w1 = ex2(l1 - mx), w2 = ex2(l2 - mx);
.Lq_have:
	s_cmpk_lt_i32 s18, 0x120
	s_cbranch_scc1 .LBB0_122
	s_addk_i32 s18, 0xffe0
	s_and_b32 s0, s18, 0xffffff00
	s_cmpk_lg_i32 s0, 0x100
	s_cbranch_scc0 .LBB0_188
	s_cmpk_gt_i32 s18, 0xff
	s_cbranch_scc0 .LBB0_122
	s_lshl_b32 s0, s18, 5
	v_add_u32_e32 v2, s0, v197
	v_ashrrev_i32_e32 v3, 31, v2
	v_lshlrev_b64 v[4:5], 5, v[2:3]
	v_lshl_add_u64 v[4:5], v[136:137], 0, v[4:5]
	v_lshlrev_b64 v[6:7], 10, v[2:3]
	v_lshl_add_u64 v[8:9], v[138:139], 0, v[6:7]
	v_lshl_add_u64 v[10:11], v[140:141], 0, v[6:7]
	s_mov_b32 s6, 0x40000
	s_mov_b32 s7, 0
	v_lshl_add_u64 v[12:13], v[4:5], 0, s[6:7]
	v_lshl_add_u64 v[14:15], v[12:13], 0, s[6:7]
	s_mov_b32 s6, 0x800000
	v_lshl_add_u64 v[16:17], v[8:9], 0, s[6:7]
	v_lshl_add_u64 v[18:19], v[16:17], 0, s[6:7]
	s_mov_b32 s6, 0x2000
	global_load_dword v30, v[4:5], off
	global_load_dword v31, v[12:13], off
	global_load_dword v32, v[14:15], off
	global_load_dword v33, v[4:5], off offset:256
	global_load_dword v34, v[12:13], off offset:256
	global_load_dword v35, v[14:15], off offset:256
	global_load_dword v36, v[4:5], off offset:512
	global_load_dword v37, v[12:13], off offset:512
	global_load_dword v38, v[14:15], off offset:512
	global_load_dword v39, v[4:5], off offset:768
	global_load_dword v40, v[12:13], off offset:768
	global_load_dword v41, v[14:15], off offset:768
	global_load_dwordx4 v[48:51], v[8:9], off
	global_load_dwordx4 v[52:55], v[16:17], off
	global_load_dwordx4 v[56:59], v[18:19], off
	v_lshl_add_u64 v[8:9], v[8:9], 0, s[6:7]
	v_lshl_add_u64 v[16:17], v[16:17], 0, s[6:7]
	v_lshl_add_u64 v[18:19], v[18:19], 0, s[6:7]
	global_load_dwordx4 v[60:63], v[8:9], off
	global_load_dwordx4 v[64:67], v[16:17], off
	global_load_dwordx4 v[68:71], v[18:19], off
	v_lshl_add_u64 v[8:9], v[8:9], 0, s[6:7]
	v_lshl_add_u64 v[16:17], v[16:17], 0, s[6:7]
	v_lshl_add_u64 v[18:19], v[18:19], 0, s[6:7]
	global_load_dwordx4 v[72:75], v[8:9], off
	global_load_dwordx4 v[76:79], v[16:17], off
	global_load_dwordx4 v[80:83], v[18:19], off
	v_lshl_add_u64 v[8:9], v[8:9], 0, s[6:7]
	v_lshl_add_u64 v[16:17], v[16:17], 0, s[6:7]
	v_lshl_add_u64 v[18:19], v[18:19], 0, s[6:7]
	global_load_dwordx4 v[84:87], v[8:9], off
	global_load_dwordx4 v[88:91], v[16:17], off
	global_load_dwordx4 v[92:95], v[18:19], off
	s_waitcnt vmcnt(12)
	v_max3_f32 v5, v30, v31, v32
	v_sub_f32_e32 v0, v30, v5
	v_exp_f32_e32 v17, v0
	v_sub_f32_e32 v0, v31, v5
	v_exp_f32_e32 v16, v0
	v_sub_f32_e32 v0, v32, v5
	v_exp_f32_e32 v20, v0
	v_add_f32_e32 v0, v17, v16
	v_add_f32_e32 v0, v20, v0
	v_div_scale_f32 v5, s[0:1], v0, v0, 1.0
	v_rcp_f32_e32 v6, v5
	s_nop 0
	v_fma_f32 v7, -v5, v6, 1.0
	v_fmac_f32_e32 v6, v7, v6
	v_div_scale_f32 v7, vcc, 1.0, v0, 1.0
	v_mul_f32_e32 v21, v7, v6
	v_fma_f32 v22, -v5, v21, v7
	v_fmac_f32_e32 v21, v22, v6
	v_fma_f32 v5, -v5, v21, v7
	v_div_fmas_f32 v5, v5, v6, v21
	v_div_fixup_f32 v0, v5, v0, 1.0
	v_mul_f32_e32 v18, v20, v0
	v_pk_mul_f32 v[16:17], v[16:17], v[0:1] op_sel_hi:[1,0]
	s_waitcnt vmcnt(9)
	v_lshlrev_b32_e32 v24, 16, v48
	v_and_b32_e32 v23, 0xffff0000, v48
	v_and_b32_e32 v25, 0xffff0000, v52
	v_lshlrev_b32_e32 v22, 16, v52
	v_lshlrev_b32_e32 v26, 16, v56
	v_and_b32_e32 v27, 0xffff0000, v56
	v_pk_mul_f32 v[24:25], v[16:17], v[24:25] op_sel:[1,0] op_sel_hi:[0,1]
	v_pk_fma_f32 v[22:23], v[16:17], v[22:23], v[24:25]
	v_pk_fma_f32 v[22:23], v[18:19], v[26:27], v[22:23] op_sel_hi:[0,1,1]
	v_cvt_pk_bf16_f32 v100, v22, v23
	v_lshlrev_b32_e32 v24, 16, v49
	v_and_b32_e32 v23, 0xffff0000, v49
	v_and_b32_e32 v25, 0xffff0000, v53
	v_lshlrev_b32_e32 v22, 16, v53
	v_lshlrev_b32_e32 v26, 16, v57
	v_and_b32_e32 v27, 0xffff0000, v57
	v_pk_mul_f32 v[24:25], v[16:17], v[24:25] op_sel:[1,0] op_sel_hi:[0,1]
	v_pk_fma_f32 v[22:23], v[16:17], v[22:23], v[24:25]
	v_pk_fma_f32 v[22:23], v[18:19], v[26:27], v[22:23] op_sel_hi:[0,1,1]
	v_cvt_pk_bf16_f32 v101, v22, v23
	v_lshlrev_b32_e32 v24, 16, v50
	v_and_b32_e32 v23, 0xffff0000, v50
	v_and_b32_e32 v25, 0xffff0000, v54
	v_lshlrev_b32_e32 v22, 16, v54
	v_lshlrev_b32_e32 v26, 16, v58
	v_and_b32_e32 v27, 0xffff0000, v58
	v_pk_mul_f32 v[24:25], v[16:17], v[24:25] op_sel:[1,0] op_sel_hi:[0,1]
	v_pk_fma_f32 v[22:23], v[16:17], v[22:23], v[24:25]
	v_pk_fma_f32 v[22:23], v[18:19], v[26:27], v[22:23] op_sel_hi:[0,1,1]
	v_cvt_pk_bf16_f32 v102, v22, v23
	v_lshlrev_b32_e32 v24, 16, v51
	v_and_b32_e32 v23, 0xffff0000, v51
	v_and_b32_e32 v25, 0xffff0000, v55
	v_lshlrev_b32_e32 v22, 16, v55
	v_lshlrev_b32_e32 v26, 16, v59
	v_and_b32_e32 v27, 0xffff0000, v59
	v_pk_mul_f32 v[24:25], v[16:17], v[24:25] op_sel:[1,0] op_sel_hi:[0,1]
	v_pk_fma_f32 v[22:23], v[16:17], v[22:23], v[24:25]
	v_pk_fma_f32 v[22:23], v[18:19], v[26:27], v[22:23] op_sel_hi:[0,1,1]
	v_cvt_pk_bf16_f32 v103, v22, v23
	global_store_dwordx4 v[10:11], v[100:103], off
	v_max3_f32 v5, v33, v34, v35
	v_sub_f32_e32 v0, v33, v5
	v_exp_f32_e32 v17, v0
	v_sub_f32_e32 v0, v34, v5
	v_exp_f32_e32 v16, v0
	v_sub_f32_e32 v0, v35, v5
	v_exp_f32_e32 v20, v0
	v_add_f32_e32 v0, v17, v16
	v_add_f32_e32 v0, v20, v0
	v_div_scale_f32 v5, s[0:1], v0, v0, 1.0
	v_rcp_f32_e32 v6, v5
	s_nop 0
	v_fma_f32 v7, -v5, v6, 1.0
	v_fmac_f32_e32 v6, v7, v6
	v_div_scale_f32 v7, vcc, 1.0, v0, 1.0
	v_mul_f32_e32 v21, v7, v6
	v_fma_f32 v22, -v5, v21, v7
	v_fmac_f32_e32 v21, v22, v6
	v_fma_f32 v5, -v5, v21, v7
	v_div_fmas_f32 v5, v5, v6, v21
	v_div_fixup_f32 v0, v5, v0, 1.0
	v_mul_f32_e32 v18, v20, v0
	v_pk_mul_f32 v[16:17], v[16:17], v[0:1] op_sel_hi:[1,0]
	s_waitcnt vmcnt(7)
; DI unsigned pk2(float lo, float hi) { f32x2_t v = {lo, hi}; bf16x2_t b = __builtin_convertvector(v, bf16x2_t); return __builtin_bit_cast(unsigned, b); }
; DI float bflo(unsigned u) { return __uint_as_float(u << 16); }
; DI float bfhi(unsigned u) { return __uint_as_float(u & 0xffff0000u); }
; DI float ex2(float x) { return __builtin_amdgcn_exp2f(x); }
; __global__ void __launch_bounds__(512, 2) mega(Params p) {
;     ...
;                         for (int ps = 0; ps < 4; ++ps) {
;                             const int tok = t0 + ps * 8 + (tid >> 6), c8 = (tid & 63) * 8, h = c8 >> 6;
;                             const float l0 = lse[(size_t)tok * 8 + h], l1 = lse[(size_t)(TC + tok) * 8 + h], l2 = lse[(size_t)(2 * TC + tok) * 8 + h];
;                             const float mx = fmaxf(l0, fmaxf(l1, l2));
;                             float w0 = ex2(l0 - mx), w1 = ex2(l1 - mx), w2 = ex2(l2 - mx);
;                             const float is = 1.0f / (w0 + w1 + w2); w0 *= is; w1 *= is; w2 *= is;
;                             const u32x4 a0 = *(const u32x4*)(og + (size_t)tok * 512 + c8), a1 = *(const u32x4*)(og + (size_t)(TC + tok) * 512 + c8), a2 = *(const u32x4*)(og + (size_t)(2 * TC + tok) * 512 + c8);
;                             u32x4 w;
;                             w.x = pk2(w0 * bflo(a0.x) + w1 * bflo(a1.x) + w2 * bflo(a2.x), w0 * bfhi(a0.x) + w1 * bfhi(a1.x) + w2 * bfhi(a2.x));
;                             w.y = pk2(w0 * bflo(a0.y) + w1 * bflo(a1.y) + w2 * bflo(a2.y), w0 * bfhi(a0.y) + w1 * bfhi(a1.y) + w2 * bfhi(a2.y));
;                             w.z = pk2(w0 * bflo(a0.z) + w1 * bflo(a1.z) + w2 * bflo(a2.z), w0 * bfhi(a0.z) + w1 * bfhi(a1.z) + w2 * bfhi(a2.z));
;                             w.w = pk2(w0 * bflo(a0.w) + w1 * bflo(a1.w) + w2 * bflo(a2.w), w0 * bfhi(a0.w) + w1 * bfhi(a1.w) + w2 * bfhi(a2.w));
;                             *(u32x4*)(oc + (size_t)tok * 512 + c8) = w;
;                         }
	v_lshlrev_b32_e32 v24, 16, v60
	v_and_b32_e32 v23, 0xffff0000, v60
	v_and_b32_e32 v25, 0xffff0000, v64
	v_lshlrev_b32_e32 v22, 16, v64
	v_lshlrev_b32_e32 v26, 16, v68
	v_and_b32_e32 v27, 0xffff0000, v68
	v_pk_mul_f32 v[24:25], v[16:17], v[24:25] op_sel:[1,0] op_sel_hi:[0,1]
	v_pk_fma_f32 v[22:23], v[16:17], v[22:23], v[24:25]
	v_pk_fma_f32 v[22:23], v[18:19], v[26:27], v[22:23] op_sel_hi:[0,1,1]
	v_cvt_pk_bf16_f32 v104, v22, v23
	v_lshlrev_b32_e32 v24, 16, v61
	v_and_b32_e32 v23, 0xffff0000, v61
	v_and_b32_e32 v25, 0xffff0000, v65
	v_lshlrev_b32_e32 v22, 16, v65
	v_lshlrev_b32_e32 v26, 16, v69
	v_and_b32_e32 v27, 0xffff0000, v69
	v_pk_mul_f32 v[24:25], v[16:17], v[24:25] op_sel:[1,0] op_sel_hi:[0,1]
	v_pk_fma_f32 v[22:23], v[16:17], v[22:23], v[24:25]
	v_pk_fma_f32 v[22:23], v[18:19], v[26:27], v[22:23] op_sel_hi:[0,1,1]
	v_cvt_pk_bf16_f32 v105, v22, v23
	v_lshlrev_b32_e32 v24, 16, v62
	v_and_b32_e32 v23, 0xffff0000, v62
	v_and_b32_e32 v25, 0xffff0000, v66
	v_lshlrev_b32_e32 v22, 16, v66
	v_lshlrev_b32_e32 v26, 16, v70
	v_and_b32_e32 v27, 0xffff0000, v70
	v_pk_mul_f32 v[24:25], v[16:17], v[24:25] op_sel:[1,0] op_sel_hi:[0,1]
	v_pk_fma_f32 v[22:23], v[16:17], v[22:23], v[24:25]
	v_pk_fma_f32 v[22:23], v[18:19], v[26:27], v[22:23] op_sel_hi:[0,1,1]
	v_cvt_pk_bf16_f32 v106, v22, v23
	v_lshlrev_b32_e32 v24, 16, v63
	v_and_b32_e32 v23, 0xffff0000, v63
	v_and_b32_e32 v25, 0xffff0000, v67
	v_lshlrev_b32_e32 v22, 16, v67
	v_lshlrev_b32_e32 v26, 16, v71
	v_and_b32_e32 v27, 0xffff0000, v71
	v_pk_mul_f32 v[24:25], v[16:17], v[24:25] op_sel:[1,0] op_sel_hi:[0,1]
	v_pk_fma_f32 v[22:23], v[16:17], v[22:23], v[24:25]
	v_pk_fma_f32 v[22:23], v[18:19], v[26:27], v[22:23] op_sel_hi:[0,1,1]
	v_cvt_pk_bf16_f32 v107, v22, v23
	v_lshl_add_u64 v[10:11], v[10:11], 0, s[6:7]
	global_store_dwordx4 v[10:11], v[104:107], off
	v_max3_f32 v5, v36, v37, v38
	v_sub_f32_e32 v0, v36, v5
	v_exp_f32_e32 v17, v0
	v_sub_f32_e32 v0, v37, v5
	v_exp_f32_e32 v16, v0
	v_sub_f32_e32 v0, v38, v5
	v_exp_f32_e32 v20, v0
	v_add_f32_e32 v0, v17, v16
	v_add_f32_e32 v0, v20, v0
	v_div_scale_f32 v5, s[0:1], v0, v0, 1.0
	v_rcp_f32_e32 v6, v5
	s_nop 0
	v_fma_f32 v7, -v5, v6, 1.0
	v_fmac_f32_e32 v6, v7, v6
	v_div_scale_f32 v7, vcc, 1.0, v0, 1.0
	v_mul_f32_e32 v21, v7, v6
	v_fma_f32 v22, -v5, v21, v7
	v_fmac_f32_e32 v21, v22, v6
	v_fma_f32 v5, -v5, v21, v7
	v_div_fmas_f32 v5, v5, v6, v21
	v_div_fixup_f32 v0, v5, v0, 1.0
	v_mul_f32_e32 v18, v20, v0
	v_pk_mul_f32 v[16:17], v[16:17], v[0:1] op_sel_hi:[1,0]
	s_waitcnt vmcnt(5)
	v_lshlrev_b32_e32 v24, 16, v72
	v_and_b32_e32 v23, 0xffff0000, v72
	v_and_b32_e32 v25, 0xffff0000, v76
	v_lshlrev_b32_e32 v22, 16, v76
	v_lshlrev_b32_e32 v26, 16, v80
	v_and_b32_e32 v27, 0xffff0000, v80
	v_pk_mul_f32 v[24:25], v[16:17], v[24:25] op_sel:[1,0] op_sel_hi:[0,1]
	v_pk_fma_f32 v[22:23], v[16:17], v[22:23], v[24:25]
	v_pk_fma_f32 v[22:23], v[18:19], v[26:27], v[22:23] op_sel_hi:[0,1,1]
	v_cvt_pk_bf16_f32 v108, v22, v23
	v_lshlrev_b32_e32 v24, 16, v73
	v_and_b32_e32 v23, 0xffff0000, v73
	v_and_b32_e32 v25, 0xffff0000, v77
	v_lshlrev_b32_e32 v22, 16, v77
	v_lshlrev_b32_e32 v26, 16, v81
	v_and_b32_e32 v27, 0xffff0000, v81
	v_pk_mul_f32 v[24:25], v[16:17], v[24:25] op_sel:[1,0] op_sel_hi:[0,1]
	v_pk_fma_f32 v[22:23], v[16:17], v[22:23], v[24:25]
	v_pk_fma_f32 v[22:23], v[18:19], v[26:27], v[22:23] op_sel_hi:[0,1,1]
	v_cvt_pk_bf16_f32 v109, v22, v23
	v_lshlrev_b32_e32 v24, 16, v74
	v_and_b32_e32 v23, 0xffff0000, v74
	v_and_b32_e32 v25, 0xffff0000, v78
	v_lshlrev_b32_e32 v22, 16, v78
	v_lshlrev_b32_e32 v26, 16, v82
	v_and_b32_e32 v27, 0xffff0000, v82
	v_pk_mul_f32 v[24:25], v[16:17], v[24:25] op_sel:[1,0] op_sel_hi:[0,1]
	v_pk_fma_f32 v[22:23], v[16:17], v[22:23], v[24:25]
	v_pk_fma_f32 v[22:23], v[18:19], v[26:27], v[22:23] op_sel_hi:[0,1,1]
	v_cvt_pk_bf16_f32 v110, v22, v23
	v_lshlrev_b32_e32 v24, 16, v75
	v_and_b32_e32 v23, 0xffff0000, v75
	v_and_b32_e32 v25, 0xffff0000, v79
	v_lshlrev_b32_e32 v22, 16, v79
	v_lshlrev_b32_e32 v26, 16, v83
	v_and_b32_e32 v27, 0xffff0000, v83
	v_pk_mul_f32 v[24:25], v[16:17], v[24:25] op_sel:[1,0] op_sel_hi:[0,1]
	v_pk_fma_f32 v[22:23], v[16:17], v[22:23], v[24:25]
	v_pk_fma_f32 v[22:23], v[18:19], v[26:27], v[22:23] op_sel_hi:[0,1,1]
	v_cvt_pk_bf16_f32 v111, v22, v23
	v_lshl_add_u64 v[10:11], v[10:11], 0, s[6:7]
	global_store_dwordx4 v[10:11], v[108:111], off
	v_max3_f32 v5, v39, v40, v41
	v_sub_f32_e32 v0, v39, v5
	v_exp_f32_e32 v17, v0
	v_sub_f32_e32 v0, v40, v5
	v_exp_f32_e32 v16, v0
	v_sub_f32_e32 v0, v41, v5
	v_exp_f32_e32 v20, v0
	v_add_f32_e32 v0, v17, v16
	v_add_f32_e32 v0, v20, v0
	v_div_scale_f32 v5, s[0:1], v0, v0, 1.0
	v_rcp_f32_e32 v6, v5
	s_nop 0
	v_fma_f32 v7, -v5, v6, 1.0
	v_fmac_f32_e32 v6, v7, v6
	v_div_scale_f32 v7, vcc, 1.0, v0, 1.0
	v_mul_f32_e32 v21, v7, v6
	v_fma_f32 v22, -v5, v21, v7
	v_fmac_f32_e32 v21, v22, v6
	v_fma_f32 v5, -v5, v21, v7
	v_div_fmas_f32 v5, v5, v6, v21
	v_div_fixup_f32 v0, v5, v0, 1.0
	v_mul_f32_e32 v18, v20, v0
	v_pk_mul_f32 v[16:17], v[16:17], v[0:1] op_sel_hi:[1,0]
	s_waitcnt vmcnt(3)
	v_lshlrev_b32_e32 v24, 16, v84
	v_and_b32_e32 v23, 0xffff0000, v84
	v_and_b32_e32 v25, 0xffff0000, v88
	v_lshlrev_b32_e32 v22, 16, v88
	v_lshlrev_b32_e32 v26, 16, v92
	v_and_b32_e32 v27, 0xffff0000, v92
	v_pk_mul_f32 v[24:25], v[16:17], v[24:25] op_sel:[1,0] op_sel_hi:[0,1]
	v_pk_fma_f32 v[22:23], v[16:17], v[22:23], v[24:25]
	v_pk_fma_f32 v[22:23], v[18:19], v[26:27], v[22:23] op_sel_hi:[0,1,1]
	v_cvt_pk_bf16_f32 v112, v22, v23
	v_lshlrev_b32_e32 v24, 16, v85
	v_and_b32_e32 v23, 0xffff0000, v85
	v_and_b32_e32 v25, 0xffff0000, v89
	v_lshlrev_b32_e32 v22, 16, v89
	v_lshlrev_b32_e32 v26, 16, v93
	v_and_b32_e32 v27, 0xffff0000, v93
	v_pk_mul_f32 v[24:25], v[16:17], v[24:25] op_sel:[1,0] op_sel_hi:[0,1]
	v_pk_fma_f32 v[22:23], v[16:17], v[22:23], v[24:25]
	v_pk_fma_f32 v[22:23], v[18:19], v[26:27], v[22:23] op_sel_hi:[0,1,1]
	v_cvt_pk_bf16_f32 v113, v22, v23
	v_lshlrev_b32_e32 v24, 16, v86
	v_and_b32_e32 v23, 0xffff0000, v86
	v_and_b32_e32 v25, 0xffff0000, v90
	v_lshlrev_b32_e32 v22, 16, v90
	v_lshlrev_b32_e32 v26, 16, v94
	v_and_b32_e32 v27, 0xffff0000, v94
	v_pk_mul_f32 v[24:25], v[16:17], v[24:25] op_sel:[1,0] op_sel_hi:[0,1]
	v_pk_fma_f32 v[22:23], v[16:17], v[22:23], v[24:25]
	v_pk_fma_f32 v[22:23], v[18:19], v[26:27], v[22:23] op_sel_hi:[0,1,1]
	v_cvt_pk_bf16_f32 v114, v22, v23
	v_lshlrev_b32_e32 v24, 16, v87
	v_and_b32_e32 v23, 0xffff0000, v87
	v_and_b32_e32 v25, 0xffff0000, v91
	v_lshlrev_b32_e32 v22, 16, v91
	v_lshlrev_b32_e32 v26, 16, v95
	v_and_b32_e32 v27, 0xffff0000, v95
	v_pk_mul_f32 v[24:25], v[16:17], v[24:25] op_sel:[1,0] op_sel_hi:[0,1]
	v_pk_fma_f32 v[22:23], v[16:17], v[22:23], v[24:25]
	v_pk_fma_f32 v[22:23], v[18:19], v[26:27], v[22:23] op_sel_hi:[0,1,1]
	v_cvt_pk_bf16_f32 v115, v22, v23
	v_lshl_add_u64 v[10:11], v[10:11], 0, s[6:7]
	global_store_dwordx4 v[10:11], v[112:115], off
	s_mov_b64 s[6:7], 0
